# all six attention softmax loops: fragment ds_reads pipelined 5 deep (counted lgkmcnt) + wave-group setprio
# speedup vs baseline: 1.0165x; 1.0017x over previous
.Lprio_2:
	v_add_u32_e32 v101, s4, v96
	s_waitcnt vmcnt(0)
	v_add_u32_e32 v100, s4, v95
	v_add_u32_e32 v99, s4, v94
	v_add_u32_e32 v98, s4, v93
	ds_read_b128 v[196:199], v101
	ds_read_b128 v[200:203], v100
	ds_read_b128 v[232:235], v101 offset:4096
	ds_read_b128 v[236:239], v100 offset:4096
	ds_read_b128 v[240:243], v99
	s_waitcnt lgkmcnt(4)
	v_mfma_f32_32x32x16_bf16 v[34:49], v[196:199], v[66:69], 0
	ds_read_b128 v[244:247], v99 offset:4096
	s_waitcnt lgkmcnt(4)
	v_mfma_f32_32x32x16_bf16 v[34:49], v[200:203], v[70:73], v[34:49]
	ds_read_b128 v[196:199], v98 offset:4096
	s_waitcnt lgkmcnt(4)
	v_mfma_f32_32x32x16_bf16 v[50:65], v[232:235], v[66:69], 0
	ds_read_b128 v[200:203], v98
	s_waitcnt lgkmcnt(4)
	v_mfma_f32_32x32x16_bf16 v[50:65], v[236:239], v[70:73], v[50:65]
	s_waitcnt lgkmcnt(3)
	v_mfma_f32_32x32x16_bf16 v[34:49], v[240:243], v[74:77], v[34:49]
	s_waitcnt lgkmcnt(2)
	v_mfma_f32_32x32x16_bf16 v[50:65], v[244:247], v[74:77], v[50:65]
	s_waitcnt lgkmcnt(1)
	v_mfma_f32_32x32x16_bf16 v[50:65], v[196:199], v[78:81], v[50:65]
	s_waitcnt lgkmcnt(0)
	v_mfma_f32_32x32x16_bf16 v[34:49], v[200:203], v[78:81], v[34:49]
	v_cmp_gt_u32_e32 vcc, 0x100, v206
	s_setprio 0
	s_cbranch_vccz .Lprio_1
	s_setprio 1
.Lprio_1:
	s_nop 1
	s_nop 8
	v_max_f32_e32 v0, v51, v51
	s_nop 1
	v_max_f32_e32 v97, v35, v35
	v_max_f32_e32 v0, v97, v0
	v_max_f32_e32 v97, v52, v52
	v_max_f32_e32 v104, v36, v36
	v_max_f32_e32 v97, v104, v97
	v_max_f32_e32 v104, v53, v53
	v_max_f32_e32 v105, v37, v37
	v_max3_f32 v0, v34, v50, v0
	v_max_f32_e32 v104, v105, v104
	v_max3_f32 v0, v0, v97, v104
	v_max_f32_e32 v97, v54, v54
	v_max_f32_e32 v104, v38, v38
	v_max_f32_e32 v97, v104, v97
	v_max_f32_e32 v104, v55, v55
	v_max_f32_e32 v105, v39, v39
	v_max_f32_e32 v104, v105, v104
	v_max3_f32 v0, v0, v97, v104
	v_max_f32_e32 v97, v56, v56
	v_max_f32_e32 v104, v40, v40
	v_max_f32_e32 v97, v104, v97
	v_max_f32_e32 v104, v57, v57
	v_max_f32_e32 v105, v41, v41
	v_max_f32_e32 v104, v105, v104
	v_max3_f32 v0, v0, v97, v104
	v_max_f32_e32 v97, v58, v58
	v_max_f32_e32 v104, v42, v42
	v_max_f32_e32 v97, v104, v97
	v_max_f32_e32 v104, v59, v59
	v_max_f32_e32 v105, v43, v43
	v_max_f32_e32 v104, v105, v104
	v_max3_f32 v0, v0, v97, v104
	v_max_f32_e32 v97, v60, v60
	v_max_f32_e32 v104, v44, v44
	v_max_f32_e32 v97, v104, v97
	v_max_f32_e32 v104, v61, v61
	v_max_f32_e32 v105, v45, v45
	v_max_f32_e32 v104, v105, v104
	v_max3_f32 v0, v0, v97, v104
	v_max_f32_e32 v97, v62, v62
	v_max_f32_e32 v104, v46, v46
	v_max_f32_e32 v97, v104, v97
	v_max_f32_e32 v104, v63, v63
	v_max_f32_e32 v105, v47, v47
	v_max_f32_e32 v104, v105, v104
	v_max3_f32 v0, v0, v97, v104
	v_max_f32_e32 v97, v64, v64
	v_max_f32_e32 v104, v48, v48
	v_max_f32_e32 v97, v104, v97
	v_max_f32_e32 v104, v65, v65
	v_max_f32_e32 v105, v49, v49
	v_max_f32_e32 v104, v105, v104
	v_max3_f32 v0, v0, v97, v104
	v_and_b32_e32 v104, 64, v221
	v_xor_b32_e32 v97, 32, v221
	v_add_u32_e32 v104, 64, v104
	v_cmp_lt_i32_e32 vcc, v97, v104
	s_nop 1
	v_cndmask_b32_e32 v97, v221, v97, vcc
	v_lshlrev_b32_e32 v104, 2, v97
	ds_bpermute_b32 v97, v104, v0
	s_waitcnt lgkmcnt(0)
	v_max3_f32 v97, v103, v0, v97
	v_sub_f32_e32 v0, v34, v97
	v_exp_f32_e32 v34, v0
	v_sub_f32_e32 v0, v50, v97
	v_exp_f32_e32 v50, v0
	v_sub_f32_e32 v0, v35, v97
	v_exp_f32_e32 v35, v0
	v_sub_f32_e32 v0, v51, v97
	v_exp_f32_e32 v51, v0
	v_sub_f32_e32 v36, v36, v97
	v_sub_f32_e32 v52, v52, v97
	v_exp_f32_e32 v36, v36
	v_exp_f32_e32 v52, v52
	v_sub_f32_e32 v0, v103, v97
	v_add_f32_e32 v103, v34, v50
	v_add_f32_e32 v103, 0, v103
	v_add_f32_e32 v105, v35, v51
	v_add_f32_e32 v103, v105, v103
	v_add_f32_e32 v105, v36, v52
	v_sub_f32_e32 v38, v38, v97
	v_sub_f32_e32 v37, v37, v97
	v_sub_f32_e32 v53, v53, v97
	v_add_f32_e32 v105, v105, v103
	v_exp_f32_e32 v103, v38
	v_sub_f32_e32 v38, v54, v97
	v_exp_f32_e32 v37, v37
	v_exp_f32_e32 v53, v53
	v_exp_f32_e32 v54, v38
	v_sub_f32_e32 v38, v39, v97
	v_exp_f32_e32 v39, v38
	v_sub_f32_e32 v38, v55, v97
	v_exp_f32_e32 v55, v38
	v_sub_f32_e32 v40, v40, v97
	v_sub_f32_e32 v56, v56, v97
	v_exp_f32_e32 v40, v40
	v_exp_f32_e32 v56, v56
	v_sub_f32_e32 v41, v41, v97
	v_sub_f32_e32 v57, v57, v97
	v_add_f32_e32 v106, v37, v53
	v_exp_f32_e32 v41, v41
	v_exp_f32_e32 v57, v57
	v_sub_f32_e32 v42, v42, v97
	v_sub_f32_e32 v58, v58, v97
	v_add_f32_e32 v38, v106, v105
	v_add_f32_e32 v105, v103, v54
	v_exp_f32_e32 v42, v42
	v_exp_f32_e32 v58, v58
	v_sub_f32_e32 v43, v43, v97
	v_sub_f32_e32 v59, v59, v97
	v_add_f32_e32 v38, v105, v38
	v_add_f32_e32 v105, v39, v55
	v_exp_f32_e32 v43, v43
	v_exp_f32_e32 v59, v59
	v_sub_f32_e32 v44, v44, v97
	v_sub_f32_e32 v60, v60, v97
	v_add_f32_e32 v38, v105, v38
	v_add_f32_e32 v105, v40, v56
	v_exp_f32_e32 v44, v44
	v_exp_f32_e32 v60, v60
	v_sub_f32_e32 v45, v45, v97
	v_sub_f32_e32 v61, v61, v97
	v_add_f32_e32 v38, v105, v38
	v_add_f32_e32 v105, v41, v57
	v_exp_f32_e32 v45, v45
	v_exp_f32_e32 v61, v61
	v_sub_f32_e32 v46, v46, v97
	v_sub_f32_e32 v62, v62, v97
	v_add_f32_e32 v38, v105, v38
	v_add_f32_e32 v105, v42, v58
	v_exp_f32_e32 v46, v46
	v_exp_f32_e32 v62, v62
	v_sub_f32_e32 v47, v47, v97
	v_sub_f32_e32 v63, v63, v97
	v_add_f32_e32 v38, v105, v38
	v_add_f32_e32 v105, v43, v59
	v_exp_f32_e32 v47, v47
	v_exp_f32_e32 v63, v63
	v_sub_f32_e32 v48, v48, v97
	v_sub_f32_e32 v64, v64, v97
	v_add_f32_e32 v38, v105, v38
	v_add_f32_e32 v105, v44, v60
	v_exp_f32_e32 v48, v48
	v_exp_f32_e32 v64, v64
	v_sub_f32_e32 v49, v49, v97
	v_sub_f32_e32 v65, v65, v97
	v_add_f32_e32 v38, v105, v38
	v_add_f32_e32 v105, v45, v61
	v_exp_f32_e32 v49, v49
	v_exp_f32_e32 v65, v65
	v_add_f32_e32 v38, v105, v38
	v_add_f32_e32 v105, v46, v62
	v_add_f32_e32 v38, v105, v38
	v_add_f32_e32 v105, v47, v63
	v_add_f32_e32 v38, v105, v38
	v_add_f32_e32 v105, v48, v64
	v_add_f32_e32 v38, v105, v38
	v_add_f32_e32 v105, v49, v65
	v_add_f32_e32 v38, v105, v38
	v_exp_f32_e32 v0, v0
	ds_bpermute_b32 v104, v104, v38
	v_cmp_neq_f32_e32 vcc, 1.0, v0
	s_cbranch_vccz .LBB0_342
	v_pk_mul_f32 v[32:33], v[32:33], v[0:1] op_sel_hi:[1,0]
	v_pk_mul_f32 v[30:31], v[30:31], v[0:1] op_sel_hi:[1,0]
	v_pk_mul_f32 v[28:29], v[28:29], v[0:1] op_sel_hi:[1,0]
	v_pk_mul_f32 v[26:27], v[26:27], v[0:1] op_sel_hi:[1,0]
	v_pk_mul_f32 v[24:25], v[24:25], v[0:1] op_sel_hi:[1,0]
	v_pk_mul_f32 v[22:23], v[22:23], v[0:1] op_sel_hi:[1,0]
	v_pk_mul_f32 v[20:21], v[20:21], v[0:1] op_sel_hi:[1,0]
	v_pk_mul_f32 v[18:19], v[18:19], v[0:1] op_sel_hi:[1,0]
	v_pk_mul_f32 v[16:17], v[16:17], v[0:1] op_sel_hi:[1,0]
	v_pk_mul_f32 v[14:15], v[14:15], v[0:1] op_sel_hi:[1,0]
	v_pk_mul_f32 v[12:13], v[12:13], v[0:1] op_sel_hi:[1,0]
	v_pk_mul_f32 v[10:11], v[10:11], v[0:1] op_sel_hi:[1,0]
	v_pk_mul_f32 v[8:9], v[8:9], v[0:1] op_sel_hi:[1,0]
	v_pk_mul_f32 v[6:7], v[6:7], v[0:1] op_sel_hi:[1,0]
	v_pk_mul_f32 v[4:5], v[4:5], v[0:1] op_sel_hi:[1,0]
	v_pk_mul_f32 v[2:3], v[2:3], v[0:1] op_sel_hi:[1,0]

.Lprio_0:
	ds_read_b128 v[196:199], v101 offset:8192
	ds_read_b128 v[200:203], v100 offset:8192
	ds_read_b128 v[232:235], v99 offset:8192
	ds_read_b128 v[236:239], v98 offset:8192
	ds_read_b128 v[240:243], v101 offset:12288
	v_cvt_pk_bf16_f32 v42, v42, v43
	v_cvt_pk_bf16_f32 v43, v44, v45
	v_cvt_pk_bf16_f32 v44, v46, v47
	v_cvt_pk_bf16_f32 v45, v48, v49
	s_waitcnt lgkmcnt(5)
	v_add_f32_e32 v38, v38, v104
	v_cvt_pk_bf16_f32 v104, v34, v35
	v_cvt_pk_bf16_f32 v105, v36, v37
	v_cvt_pk_bf16_f32 v106, v103, v39
	v_cvt_pk_bf16_f32 v107, v40, v41
	v_cvt_pk_bf16_f32 v50, v50, v51
	v_cvt_pk_bf16_f32 v51, v52, v53
	s_waitcnt lgkmcnt(4)
	v_mfma_f32_32x32x16_bf16 v[2:17], v[196:199], v[104:107], v[2:17]
	ds_read_b128 v[244:247], v100 offset:12288
	v_cvt_pk_bf16_f32 v52, v54, v55
	v_cvt_pk_bf16_f32 v53, v56, v57
	v_cvt_pk_bf16_f32 v34, v58, v59
	v_cvt_pk_bf16_f32 v35, v60, v61
	v_cvt_pk_bf16_f32 v36, v62, v63
	v_cvt_pk_bf16_f32 v37, v64, v65
	s_waitcnt lgkmcnt(4)
	v_mfma_f32_32x32x16_bf16 v[2:17], v[200:203], v[42:45], v[2:17]
	ds_read_b128 v[196:199], v99 offset:12288
	s_add_i32 s5, s5, 1
	s_addk_i32 s4, 0x4000
	v_fmac_f32_e32 v38, v102, v0
	s_cmp_lg_u32 s4, 0x10000
	s_waitcnt lgkmcnt(4)
	v_mfma_f32_32x32x16_bf16 v[2:17], v[232:235], v[50:53], v[2:17]
	ds_read_b128 v[200:203], v98 offset:12288
	s_waitcnt lgkmcnt(4)
	v_mfma_f32_32x32x16_bf16 v[2:17], v[236:239], v[34:37], v[2:17]
	s_waitcnt lgkmcnt(3)
	v_mfma_f32_32x32x16_bf16 v[18:33], v[240:243], v[104:107], v[18:33]
	s_waitcnt lgkmcnt(2)
	v_mfma_f32_32x32x16_bf16 v[18:33], v[244:247], v[42:45], v[18:33]
	s_waitcnt lgkmcnt(1)
	v_mfma_f32_32x32x16_bf16 v[18:33], v[196:199], v[50:53], v[18:33]
	s_waitcnt lgkmcnt(0)
	v_mfma_f32_32x32x16_bf16 v[18:33], v[200:203], v[34:37], v[18:33]
	s_cbranch_scc1 .LBB0_330
	s_mov_b32 s0, 0x3fb8aa3b
	v_fma_f32 v0, v91, s0, -v97
	v_exp_f32_e32 v0, v0
	v_readlane_b32 s36, v253, 33
	v_lshlrev_b64 v[34:35], 12, v[82:83]
	v_readlane_b32 s48, v253, 45
	v_add_f32_e32 v36, v0, v38
	v_div_scale_f32 v37, s[0:1], v36, v36, 1.0
	v_rcp_f32_e32 v38, v37
	v_readlane_b32 s49, v253, 46
	v_lshlrev_b32_e32 v0, 1, v84
	v_readlane_b32 s37, v253, 34
	v_lshl_add_u64 v[34:35], s[48:49], 0, v[34:35]
	v_lshl_add_u64 v[34:35], v[34:35], 0, v[0:1]
	v_fma_f32 v0, -v37, v38, 1.0
	v_fmac_f32_e32 v38, v0, v38
	v_div_scale_f32 v0, vcc, 1.0, v36, 1.0
	v_mul_f32_e32 v39, v0, v38
	v_fma_f32 v40, -v37, v39, v0
	v_fmac_f32_e32 v39, v40, v38
	v_fma_f32 v0, -v37, v39, v0
	v_div_fmas_f32 v0, v0, v38, v39
	v_div_fixup_f32 v36, v0, v36, 1.0
	v_lshlrev_b32_e32 v0, 12, v90
	v_lshl_add_u64 v[34:35], v[34:35], 0, v[0:1]
	v_lshlrev_b32_e32 v0, 3, v85
	v_pk_mul_f32 v[2:3], v[36:37], v[2:3] op_sel_hi:[0,1]
	v_pk_mul_f32 v[4:5], v[36:37], v[4:5] op_sel_hi:[0,1]
	v_lshl_add_u64 v[34:35], v[34:35], 0, v[0:1]
	v_cvt_pk_bf16_f32 v2, v2, v3
	v_cvt_pk_bf16_f32 v3, v4, v5
	global_store_dwordx2 v[34:35], v[2:3], off offset:2048
	v_pk_mul_f32 v[2:3], v[36:37], v[6:7] op_sel_hi:[0,1]
	v_pk_mul_f32 v[4:5], v[36:37], v[8:9] op_sel_hi:[0,1]
	v_cvt_pk_bf16_f32 v2, v2, v3
	v_cvt_pk_bf16_f32 v3, v4, v5
	global_store_dwordx2 v[34:35], v[2:3], off offset:2064
	v_pk_mul_f32 v[2:3], v[36:37], v[10:11] op_sel_hi:[0,1]
	v_pk_mul_f32 v[4:5], v[36:37], v[12:13] op_sel_hi:[0,1]
	v_cvt_pk_bf16_f32 v2, v2, v3
	v_cvt_pk_bf16_f32 v3, v4, v5
	global_store_dwordx2 v[34:35], v[2:3], off offset:2080
	v_pk_mul_f32 v[2:3], v[36:37], v[14:15] op_sel_hi:[0,1]
	v_pk_mul_f32 v[4:5], v[36:37], v[16:17] op_sel_hi:[0,1]
	v_cvt_pk_bf16_f32 v2, v2, v3
	v_cvt_pk_bf16_f32 v3, v4, v5
	global_store_dwordx2 v[34:35], v[2:3], off offset:2096
	v_pk_mul_f32 v[2:3], v[36:37], v[18:19] op_sel_hi:[0,1]
	v_pk_mul_f32 v[4:5], v[36:37], v[20:21] op_sel_hi:[0,1]
	v_cvt_pk_bf16_f32 v2, v2, v3
	v_cvt_pk_bf16_f32 v3, v4, v5
	global_store_dwordx2 v[34:35], v[2:3], off offset:2112
	v_pk_mul_f32 v[2:3], v[36:37], v[22:23] op_sel_hi:[0,1]
	v_pk_mul_f32 v[4:5], v[36:37], v[24:25] op_sel_hi:[0,1]
	v_cvt_pk_bf16_f32 v2, v2, v3
	v_cvt_pk_bf16_f32 v3, v4, v5
	global_store_dwordx2 v[34:35], v[2:3], off offset:2128
	v_pk_mul_f32 v[2:3], v[36:37], v[26:27] op_sel_hi:[0,1]
	v_pk_mul_f32 v[4:5], v[36:37], v[28:29] op_sel_hi:[0,1]
	v_cvt_pk_bf16_f32 v2, v2, v3
	v_cvt_pk_bf16_f32 v3, v4, v5
	global_store_dwordx2 v[34:35], v[2:3], off offset:2144
	v_pk_mul_f32 v[2:3], v[36:37], v[30:31] op_sel_hi:[0,1]
	v_pk_mul_f32 v[4:5], v[36:37], v[32:33] op_sel_hi:[0,1]
	v_cvt_pk_bf16_f32 v2, v2, v3
	v_cvt_pk_bf16_f32 v3, v4, v5
	v_readlane_b32 s38, v253, 35
	v_readlane_b32 s39, v253, 36
	v_readlane_b32 s40, v253, 37
	v_readlane_b32 s41, v253, 38
	v_readlane_b32 s42, v253, 39
	v_readlane_b32 s43, v253, 40
	v_readlane_b32 s44, v253, 41
	v_readlane_b32 s45, v253, 42
	v_readlane_b32 s46, v253, 43
	v_readlane_b32 s47, v253, 44
	v_readlane_b32 s50, v253, 47
	v_readlane_b32 s51, v253, 48
	global_store_dwordx2 v[34:35], v[2:3], off offset:2160
	s_mov_b64 s[0:1], 0

.Lprio_8:
	v_add_u32_e32 v99, s4, v94
	s_waitcnt vmcnt(0)
	v_add_u32_e32 v98, s4, v93
	v_add_u32_e32 v97, s4, v92
	v_add_u32_e32 v95, s4, v91
	ds_read_b128 v[196:199], v99
	ds_read_b128 v[200:203], v98
	ds_read_b128 v[232:235], v99 offset:4096
	ds_read_b128 v[236:239], v98 offset:4096
	ds_read_b128 v[240:243], v97
	s_waitcnt lgkmcnt(4)
	v_mfma_f32_32x32x16_bf16 v[34:49], v[196:199], v[66:69], 0
	ds_read_b128 v[244:247], v97 offset:4096
	s_waitcnt lgkmcnt(4)
	v_mfma_f32_32x32x16_bf16 v[34:49], v[200:203], v[70:73], v[34:49]
	ds_read_b128 v[196:199], v95 offset:4096
	s_waitcnt lgkmcnt(4)
	v_mfma_f32_32x32x16_bf16 v[50:65], v[232:235], v[66:69], 0
	ds_read_b128 v[200:203], v95
	s_waitcnt lgkmcnt(4)
	v_mfma_f32_32x32x16_bf16 v[50:65], v[236:239], v[70:73], v[50:65]
	s_waitcnt lgkmcnt(3)
	v_mfma_f32_32x32x16_bf16 v[34:49], v[240:243], v[74:77], v[34:49]
	s_waitcnt lgkmcnt(2)
	v_mfma_f32_32x32x16_bf16 v[50:65], v[244:247], v[74:77], v[50:65]
	s_waitcnt lgkmcnt(1)
	v_mfma_f32_32x32x16_bf16 v[50:65], v[196:199], v[78:81], v[50:65]
	s_waitcnt lgkmcnt(0)
	v_mfma_f32_32x32x16_bf16 v[34:49], v[200:203], v[78:81], v[34:49]
	v_cmp_gt_u32_e32 vcc, 0x100, v206
	s_setprio 0
	s_cbranch_vccz .Lprio_7
	s_setprio 1
.Lprio_7:
	s_nop 1
	s_nop 8
	v_max_f32_e32 v0, v51, v51
	s_nop 1
	v_max_f32_e32 v96, v35, v35
	v_max_f32_e32 v0, v96, v0
	v_max_f32_e32 v96, v52, v52
	v_max_f32_e32 v102, v36, v36
	v_max_f32_e32 v96, v102, v96
	v_max_f32_e32 v102, v53, v53
	v_max_f32_e32 v103, v37, v37
	v_max3_f32 v0, v34, v50, v0
	v_max_f32_e32 v102, v103, v102
	v_max3_f32 v0, v0, v96, v102
	v_max_f32_e32 v96, v54, v54
	v_max_f32_e32 v102, v38, v38
	v_max_f32_e32 v96, v102, v96
	v_max_f32_e32 v102, v55, v55
	v_max_f32_e32 v103, v39, v39
	v_max_f32_e32 v102, v103, v102
	v_max3_f32 v0, v0, v96, v102
	v_max_f32_e32 v96, v56, v56
	v_max_f32_e32 v102, v40, v40
	v_max_f32_e32 v96, v102, v96
	v_max_f32_e32 v102, v57, v57
	v_max_f32_e32 v103, v41, v41
	v_max_f32_e32 v102, v103, v102
	v_max3_f32 v0, v0, v96, v102
	v_max_f32_e32 v96, v58, v58
	v_max_f32_e32 v102, v42, v42
	v_max_f32_e32 v96, v102, v96
	v_max_f32_e32 v102, v59, v59
	v_max_f32_e32 v103, v43, v43
	v_max_f32_e32 v102, v103, v102
	v_max3_f32 v0, v0, v96, v102
	v_max_f32_e32 v96, v60, v60
	v_max_f32_e32 v102, v44, v44
	v_max_f32_e32 v96, v102, v96
	v_max_f32_e32 v102, v61, v61
	v_max_f32_e32 v103, v45, v45
	v_max_f32_e32 v102, v103, v102
	v_max3_f32 v0, v0, v96, v102
	v_max_f32_e32 v96, v62, v62
	v_max_f32_e32 v102, v46, v46
	v_max_f32_e32 v96, v102, v96
	v_max_f32_e32 v102, v63, v63
	v_max_f32_e32 v103, v47, v47
	v_max_f32_e32 v102, v103, v102
	v_max3_f32 v0, v0, v96, v102
	v_max_f32_e32 v96, v64, v64
	v_max_f32_e32 v102, v48, v48
	v_max_f32_e32 v96, v102, v96
	v_max_f32_e32 v102, v65, v65
	v_max_f32_e32 v103, v49, v49
	v_max_f32_e32 v102, v103, v102
	v_max3_f32 v0, v0, v96, v102
	v_and_b32_e32 v102, 64, v221
	v_xor_b32_e32 v96, 32, v221
	v_add_u32_e32 v102, 64, v102
	v_cmp_lt_i32_e32 vcc, v96, v102
	s_nop 1
	v_cndmask_b32_e32 v96, v221, v96, vcc
	v_lshlrev_b32_e32 v102, 2, v96
	ds_bpermute_b32 v96, v102, v0
	s_waitcnt lgkmcnt(0)
	v_max3_f32 v96, v101, v0, v96
	v_sub_f32_e32 v0, v34, v96
	v_exp_f32_e32 v34, v0
	v_sub_f32_e32 v0, v50, v96
	v_exp_f32_e32 v50, v0
	v_sub_f32_e32 v0, v35, v96
	v_exp_f32_e32 v35, v0
	v_sub_f32_e32 v0, v51, v96
	v_exp_f32_e32 v51, v0
	v_sub_f32_e32 v36, v36, v96
	v_sub_f32_e32 v52, v52, v96
	v_exp_f32_e32 v36, v36
	v_exp_f32_e32 v52, v52
	v_sub_f32_e32 v0, v101, v96
	v_add_f32_e32 v101, v34, v50
	v_add_f32_e32 v101, 0, v101
	v_add_f32_e32 v103, v35, v51
	v_add_f32_e32 v101, v103, v101
	v_add_f32_e32 v103, v36, v52
	v_sub_f32_e32 v38, v38, v96
	v_sub_f32_e32 v37, v37, v96
	v_sub_f32_e32 v53, v53, v96
	v_add_f32_e32 v103, v103, v101
	v_exp_f32_e32 v101, v38
	v_sub_f32_e32 v38, v54, v96
	v_exp_f32_e32 v37, v37
	v_exp_f32_e32 v53, v53
	v_exp_f32_e32 v54, v38
	v_sub_f32_e32 v38, v39, v96
	v_exp_f32_e32 v39, v38
	v_sub_f32_e32 v38, v55, v96
	v_exp_f32_e32 v55, v38
	v_sub_f32_e32 v40, v40, v96
	v_sub_f32_e32 v56, v56, v96
	v_exp_f32_e32 v40, v40
	v_exp_f32_e32 v56, v56
	v_sub_f32_e32 v41, v41, v96
	v_sub_f32_e32 v57, v57, v96
	v_add_f32_e32 v104, v37, v53
	v_exp_f32_e32 v41, v41
	v_exp_f32_e32 v57, v57
	v_sub_f32_e32 v42, v42, v96
	v_sub_f32_e32 v58, v58, v96
	v_add_f32_e32 v38, v104, v103
	v_add_f32_e32 v103, v101, v54
	v_exp_f32_e32 v42, v42
	v_exp_f32_e32 v58, v58
	v_sub_f32_e32 v43, v43, v96
	v_sub_f32_e32 v59, v59, v96
	v_add_f32_e32 v38, v103, v38
	v_add_f32_e32 v103, v39, v55
	v_exp_f32_e32 v43, v43
	v_exp_f32_e32 v59, v59
	v_sub_f32_e32 v44, v44, v96
	v_sub_f32_e32 v60, v60, v96
	v_add_f32_e32 v38, v103, v38
	v_add_f32_e32 v103, v40, v56
	v_exp_f32_e32 v44, v44
	v_exp_f32_e32 v60, v60
	v_sub_f32_e32 v45, v45, v96
	v_sub_f32_e32 v61, v61, v96
	v_add_f32_e32 v38, v103, v38
	v_add_f32_e32 v103, v41, v57
	v_exp_f32_e32 v45, v45
	v_exp_f32_e32 v61, v61
	v_sub_f32_e32 v46, v46, v96
	v_sub_f32_e32 v62, v62, v96
	v_add_f32_e32 v38, v103, v38
	v_add_f32_e32 v103, v42, v58
	v_exp_f32_e32 v46, v46
	v_exp_f32_e32 v62, v62
	v_sub_f32_e32 v47, v47, v96
	v_sub_f32_e32 v63, v63, v96
	v_add_f32_e32 v38, v103, v38
	v_add_f32_e32 v103, v43, v59
	v_exp_f32_e32 v47, v47
	v_exp_f32_e32 v63, v63
	v_sub_f32_e32 v48, v48, v96
	v_sub_f32_e32 v64, v64, v96
	v_add_f32_e32 v38, v103, v38
	v_add_f32_e32 v103, v44, v60
	v_exp_f32_e32 v48, v48
	v_exp_f32_e32 v64, v64
	v_sub_f32_e32 v49, v49, v96
	v_sub_f32_e32 v65, v65, v96
	v_add_f32_e32 v38, v103, v38
	v_add_f32_e32 v103, v45, v61
	v_exp_f32_e32 v49, v49
	v_exp_f32_e32 v65, v65
	v_add_f32_e32 v38, v103, v38
	v_add_f32_e32 v103, v46, v62
	v_add_f32_e32 v38, v103, v38
	v_add_f32_e32 v103, v47, v63
	v_add_f32_e32 v38, v103, v38
	v_add_f32_e32 v103, v48, v64
	v_add_f32_e32 v38, v103, v38
	v_add_f32_e32 v103, v49, v65
	v_add_f32_e32 v38, v103, v38
	v_exp_f32_e32 v0, v0
	ds_bpermute_b32 v102, v102, v38
	v_cmp_neq_f32_e32 vcc, 1.0, v0
	s_cbranch_vccz .LBB0_371
	v_pk_mul_f32 v[32:33], v[32:33], v[0:1] op_sel_hi:[1,0]
	v_pk_mul_f32 v[30:31], v[30:31], v[0:1] op_sel_hi:[1,0]
	v_pk_mul_f32 v[28:29], v[28:29], v[0:1] op_sel_hi:[1,0]
	v_pk_mul_f32 v[26:27], v[26:27], v[0:1] op_sel_hi:[1,0]
	v_pk_mul_f32 v[24:25], v[24:25], v[0:1] op_sel_hi:[1,0]
	v_pk_mul_f32 v[22:23], v[22:23], v[0:1] op_sel_hi:[1,0]
	v_pk_mul_f32 v[20:21], v[20:21], v[0:1] op_sel_hi:[1,0]
	v_pk_mul_f32 v[18:19], v[18:19], v[0:1] op_sel_hi:[1,0]
	v_pk_mul_f32 v[16:17], v[16:17], v[0:1] op_sel_hi:[1,0]
	v_pk_mul_f32 v[14:15], v[14:15], v[0:1] op_sel_hi:[1,0]
	v_pk_mul_f32 v[12:13], v[12:13], v[0:1] op_sel_hi:[1,0]
	v_pk_mul_f32 v[10:11], v[10:11], v[0:1] op_sel_hi:[1,0]
	v_pk_mul_f32 v[8:9], v[8:9], v[0:1] op_sel_hi:[1,0]
	v_pk_mul_f32 v[6:7], v[6:7], v[0:1] op_sel_hi:[1,0]
	v_pk_mul_f32 v[4:5], v[4:5], v[0:1] op_sel_hi:[1,0]
	v_pk_mul_f32 v[2:3], v[2:3], v[0:1] op_sel_hi:[1,0]

.Lprio_6:
	ds_read_b128 v[196:199], v99 offset:8192
	ds_read_b128 v[200:203], v98 offset:8192
	ds_read_b128 v[232:235], v97 offset:8192
	ds_read_b128 v[236:239], v95 offset:8192
	ds_read_b128 v[240:243], v99 offset:12288
	v_cvt_pk_bf16_f32 v42, v42, v43
	v_cvt_pk_bf16_f32 v43, v44, v45
	v_cvt_pk_bf16_f32 v44, v46, v47
	v_cvt_pk_bf16_f32 v45, v48, v49
	s_waitcnt lgkmcnt(5)
	v_add_f32_e32 v38, v38, v102
	v_cvt_pk_bf16_f32 v102, v34, v35
	v_cvt_pk_bf16_f32 v103, v36, v37
	v_cvt_pk_bf16_f32 v104, v101, v39
	v_cvt_pk_bf16_f32 v105, v40, v41
	v_cvt_pk_bf16_f32 v50, v50, v51
	v_cvt_pk_bf16_f32 v51, v52, v53
	s_waitcnt lgkmcnt(4)
	v_mfma_f32_32x32x16_bf16 v[2:17], v[196:199], v[102:105], v[2:17]
	ds_read_b128 v[244:247], v98 offset:12288
	v_cvt_pk_bf16_f32 v52, v54, v55
	v_cvt_pk_bf16_f32 v53, v56, v57
	v_cvt_pk_bf16_f32 v34, v58, v59
	v_cvt_pk_bf16_f32 v35, v60, v61
	v_cvt_pk_bf16_f32 v36, v62, v63
	v_cvt_pk_bf16_f32 v37, v64, v65
	s_waitcnt lgkmcnt(4)
	v_mfma_f32_32x32x16_bf16 v[2:17], v[200:203], v[42:45], v[2:17]
	ds_read_b128 v[196:199], v97 offset:12288
	s_add_i32 s5, s5, 1
	s_addk_i32 s4, 0x4000
	v_fmac_f32_e32 v38, v100, v0
	s_cmp_lg_u32 s4, 0x10000
	s_waitcnt lgkmcnt(4)
	v_mfma_f32_32x32x16_bf16 v[2:17], v[232:235], v[50:53], v[2:17]
	ds_read_b128 v[200:203], v95 offset:12288
	s_waitcnt lgkmcnt(4)
	v_mfma_f32_32x32x16_bf16 v[2:17], v[236:239], v[34:37], v[2:17]
	s_waitcnt lgkmcnt(3)
	v_mfma_f32_32x32x16_bf16 v[18:33], v[240:243], v[102:105], v[18:33]
	s_waitcnt lgkmcnt(2)
	v_mfma_f32_32x32x16_bf16 v[18:33], v[244:247], v[42:45], v[18:33]
	s_waitcnt lgkmcnt(1)
	v_mfma_f32_32x32x16_bf16 v[18:33], v[196:199], v[50:53], v[18:33]
	s_waitcnt lgkmcnt(0)
	v_mfma_f32_32x32x16_bf16 v[18:33], v[200:203], v[34:37], v[18:33]
	s_cbranch_scc1 .LBB0_359
	v_div_scale_f32 v0, s[0:1], v38, v38, 1.0
	v_rcp_f32_e32 v36, v0
	v_readlane_b32 s36, v253, 33
	v_lshlrev_b64 v[34:35], 12, v[82:83]
	v_readlane_b32 s48, v253, 45
	v_fma_f32 v37, -v0, v36, 1.0
	v_fmac_f32_e32 v36, v37, v36
	v_div_scale_f32 v37, vcc, 1.0, v38, 1.0
	v_mul_f32_e32 v39, v37, v36
	v_fma_f32 v40, -v0, v39, v37
	v_fmac_f32_e32 v39, v40, v36
	v_readlane_b32 s49, v253, 46
	v_fma_f32 v0, -v0, v39, v37
	s_lshl_b32 s96, s10, 1
	v_lshl_add_u64 v[34:35], s[48:49], 0, v[34:35]
	v_div_fmas_f32 v0, v0, v36, v39
	v_lshl_add_u64 v[34:35], v[34:35], 0, s[96:97]
	v_div_fixup_f32 v36, v0, v38, 1.0
	v_lshlrev_b32_e32 v0, 12, v89
	v_lshl_add_u64 v[34:35], v[34:35], 0, v[0:1]
	v_lshlrev_b32_e32 v0, 3, v88
	v_pk_mul_f32 v[2:3], v[36:37], v[2:3] op_sel_hi:[0,1]
	v_pk_mul_f32 v[4:5], v[36:37], v[4:5] op_sel_hi:[0,1]
	v_lshl_add_u64 v[34:35], v[34:35], 0, v[0:1]
	v_cvt_pk_bf16_f32 v2, v2, v3
	v_cvt_pk_bf16_f32 v3, v4, v5
	global_store_dwordx2 v[34:35], v[2:3], off
	v_pk_mul_f32 v[2:3], v[36:37], v[6:7] op_sel_hi:[0,1]
	v_pk_mul_f32 v[4:5], v[36:37], v[8:9] op_sel_hi:[0,1]
	v_cvt_pk_bf16_f32 v2, v2, v3
	v_cvt_pk_bf16_f32 v3, v4, v5
	global_store_dwordx2 v[34:35], v[2:3], off offset:16
	v_pk_mul_f32 v[2:3], v[36:37], v[10:11] op_sel_hi:[0,1]
	v_pk_mul_f32 v[4:5], v[36:37], v[12:13] op_sel_hi:[0,1]
	v_cvt_pk_bf16_f32 v2, v2, v3
	v_cvt_pk_bf16_f32 v3, v4, v5
	global_store_dwordx2 v[34:35], v[2:3], off offset:32
	v_pk_mul_f32 v[2:3], v[36:37], v[14:15] op_sel_hi:[0,1]
	v_pk_mul_f32 v[4:5], v[36:37], v[16:17] op_sel_hi:[0,1]
	v_cvt_pk_bf16_f32 v2, v2, v3
	v_cvt_pk_bf16_f32 v3, v4, v5
	global_store_dwordx2 v[34:35], v[2:3], off offset:48
	v_pk_mul_f32 v[2:3], v[36:37], v[18:19] op_sel_hi:[0,1]
	v_pk_mul_f32 v[4:5], v[36:37], v[20:21] op_sel_hi:[0,1]
	v_cvt_pk_bf16_f32 v2, v2, v3
	v_cvt_pk_bf16_f32 v3, v4, v5
	global_store_dwordx2 v[34:35], v[2:3], off offset:64
	v_pk_mul_f32 v[2:3], v[36:37], v[22:23] op_sel_hi:[0,1]
	v_pk_mul_f32 v[4:5], v[36:37], v[24:25] op_sel_hi:[0,1]
	v_cvt_pk_bf16_f32 v2, v2, v3
	v_cvt_pk_bf16_f32 v3, v4, v5
	global_store_dwordx2 v[34:35], v[2:3], off offset:80
	v_pk_mul_f32 v[2:3], v[36:37], v[26:27] op_sel_hi:[0,1]
	v_pk_mul_f32 v[4:5], v[36:37], v[28:29] op_sel_hi:[0,1]
	v_cvt_pk_bf16_f32 v2, v2, v3
	v_cvt_pk_bf16_f32 v3, v4, v5
	global_store_dwordx2 v[34:35], v[2:3], off offset:96
	v_pk_mul_f32 v[2:3], v[36:37], v[30:31] op_sel_hi:[0,1]
	v_pk_mul_f32 v[4:5], v[36:37], v[32:33] op_sel_hi:[0,1]
	v_cvt_pk_bf16_f32 v2, v2, v3
	v_cvt_pk_bf16_f32 v3, v4, v5
	v_readlane_b32 s96, v254, 51
	v_readlane_b32 s37, v253, 34
	v_readlane_b32 s38, v253, 35
	v_readlane_b32 s39, v253, 36
	v_readlane_b32 s40, v253, 37
	v_readlane_b32 s41, v253, 38
	v_readlane_b32 s42, v253, 39
	v_readlane_b32 s43, v253, 40
	v_readlane_b32 s44, v253, 41
	v_readlane_b32 s45, v253, 42
	v_readlane_b32 s46, v253, 43
	v_readlane_b32 s47, v253, 44
	v_readlane_b32 s50, v253, 47
	v_readlane_b32 s51, v253, 48
	global_store_dwordx2 v[34:35], v[2:3], off offset:112

.Lprio_14:
	s_and_b32 s8, s17, 0xc000
	v_or_b32_e32 v50, s8, v94
	s_waitcnt vmcnt(0)
	v_or_b32_e32 v204, s8, v95
	v_or_b32_e32 v205, s8, v96
	v_or_b32_e32 v248, s8, v97
	ds_read_b128 v[196:199], v50
	ds_read_b128 v[200:203], v204
	ds_read_b128 v[232:235], v50 offset:4096
	ds_read_b128 v[236:239], v204 offset:4096
	ds_read_b128 v[240:243], v205
	s_andn2_b64 vcc, exec, s[0:1]
	s_waitcnt lgkmcnt(4)
	v_mfma_f32_32x32x16_bf16 v[34:49], v[196:199], v[66:69], 0
	ds_read_b128 v[244:247], v205 offset:4096
	s_waitcnt lgkmcnt(4)
	v_mfma_f32_32x32x16_bf16 v[34:49], v[200:203], v[70:73], v[34:49]
	ds_read_b128 v[196:199], v248
	s_waitcnt lgkmcnt(4)
	v_mfma_f32_32x32x16_bf16 v[50:65], v[232:235], v[66:69], 0
	ds_read_b128 v[200:203], v248 offset:4096
	s_waitcnt lgkmcnt(4)
	v_mfma_f32_32x32x16_bf16 v[50:65], v[236:239], v[70:73], v[50:65]
	s_waitcnt lgkmcnt(3)
	v_mfma_f32_32x32x16_bf16 v[34:49], v[240:243], v[74:77], v[34:49]
	s_waitcnt lgkmcnt(2)
	v_mfma_f32_32x32x16_bf16 v[50:65], v[244:247], v[74:77], v[50:65]
	s_waitcnt lgkmcnt(1)
	v_mfma_f32_32x32x16_bf16 v[34:49], v[196:199], v[78:81], v[34:49]
	s_waitcnt lgkmcnt(0)
	v_mfma_f32_32x32x16_bf16 v[50:65], v[200:203], v[78:81], v[50:65]
	s_nop 1
	s_cbranch_vccnz .LBB0_405
	s_lshl_b32 s0, s54, 6
	s_sub_i32 s1, s9, s10
	s_add_i32 s0, s1, s0
	s_addk_i32 s0, 0xf000
	v_sub_u32_e32 v101, s0, v91
	v_add_u32_e32 v101, 63, v101
	v_subrev_u32_e32 v102, s0, v98
	v_max_i32_e32 v101, v101, v102
	s_movk_i32 s1, 0x80
	v_cmp_lt_i32_e32 vcc, s1, v101
	s_and_saveexec_b64 s[4:5], vcc
	s_cbranch_execz .LBB0_404
	v_add_u32_e32 v101, s0, v99
	s_movk_i32 s0, 0x101
	v_cmp_gt_u32_e32 vcc, s0, v101
	v_add_u32_e32 v102, 0xffffff1f, v101
	s_movk_i32 s0, 0xfefe
	v_cndmask_b32_e32 v34, v215, v34, vcc
	v_cmp_lt_u32_e32 vcc, s0, v102
	v_add_u32_e32 v102, 0xffffff00, v101
	s_nop 0
	v_cndmask_b32_e32 v50, v215, v50, vcc
	v_cmp_lt_u32_e32 vcc, s0, v102
	v_add_u32_e32 v102, 0xffffff20, v101
	s_nop 0
	v_cndmask_b32_e32 v35, v215, v35, vcc
	v_cmp_lt_u32_e32 vcc, s0, v102
	v_add_u32_e32 v102, 0xffffff01, v101
	s_nop 0
	v_cndmask_b32_e32 v51, v215, v51, vcc
	v_cmp_lt_u32_e32 vcc, s0, v102
	v_add_u32_e32 v102, 0xffffff21, v101
	s_nop 0
	v_cndmask_b32_e32 v36, v215, v36, vcc
	v_cmp_lt_u32_e32 vcc, s0, v102
	v_add_u32_e32 v102, 0xffffff02, v101
	s_nop 0
	v_cndmask_b32_e32 v52, v215, v52, vcc
	v_cmp_lt_u32_e32 vcc, s0, v102
	v_add_u32_e32 v102, 0xffffff22, v101
	s_nop 0
	v_cndmask_b32_e32 v37, v215, v37, vcc
	v_cmp_lt_u32_e32 vcc, s0, v102
	v_add_u32_e32 v102, 0xffffff07, v101
	s_nop 0
	v_cndmask_b32_e32 v53, v215, v53, vcc
	v_cmp_lt_u32_e32 vcc, s0, v102
	v_add_u32_e32 v102, 0xffffff27, v101
	s_nop 0
	v_cndmask_b32_e32 v38, v215, v38, vcc
	v_cmp_lt_u32_e32 vcc, s0, v102
	v_add_u32_e32 v102, 0xffffff08, v101
	s_nop 0
	v_cndmask_b32_e32 v54, v215, v54, vcc
	v_cmp_lt_u32_e32 vcc, s0, v102
	v_add_u32_e32 v102, 0xffffff28, v101
	s_nop 0
	v_cndmask_b32_e32 v39, v215, v39, vcc
	v_cmp_lt_u32_e32 vcc, s0, v102
	v_add_u32_e32 v102, 0xffffff09, v101
	s_nop 0
	v_cndmask_b32_e32 v55, v215, v55, vcc
	v_cmp_lt_u32_e32 vcc, s0, v102
	v_add_u32_e32 v102, 0xffffff29, v101
	s_nop 0
	v_cndmask_b32_e32 v40, v215, v40, vcc
	v_cmp_lt_u32_e32 vcc, s0, v102
	v_add_u32_e32 v102, 0xffffff0a, v101
	s_nop 0
	v_cndmask_b32_e32 v56, v215, v56, vcc
	v_cmp_lt_u32_e32 vcc, s0, v102
	v_add_u32_e32 v102, 0xffffff2a, v101
	s_nop 0
	v_cndmask_b32_e32 v41, v215, v41, vcc
	v_cmp_lt_u32_e32 vcc, s0, v102
	v_add_u32_e32 v102, 0xffffff0f, v101
	s_nop 0
	v_cndmask_b32_e32 v57, v215, v57, vcc
	v_cmp_lt_u32_e32 vcc, s0, v102
	v_add_u32_e32 v102, 0xffffff2f, v101
	s_nop 0
	v_cndmask_b32_e32 v42, v215, v42, vcc
	v_cmp_lt_u32_e32 vcc, s0, v102
	v_add_u32_e32 v102, 0xffffff10, v101
	s_nop 0
	v_cndmask_b32_e32 v58, v215, v58, vcc
	v_cmp_lt_u32_e32 vcc, s0, v102
	v_add_u32_e32 v102, 0xffffff30, v101
	s_nop 0
	v_cndmask_b32_e32 v43, v215, v43, vcc
	v_cmp_lt_u32_e32 vcc, s0, v102
	v_add_u32_e32 v102, 0xffffff11, v101
	s_nop 0
	v_cndmask_b32_e32 v59, v215, v59, vcc
	v_cmp_lt_u32_e32 vcc, s0, v102
	v_add_u32_e32 v102, 0xffffff31, v101
	s_nop 0
	v_cndmask_b32_e32 v44, v215, v44, vcc
	v_cmp_lt_u32_e32 vcc, s0, v102
	v_add_u32_e32 v102, 0xffffff12, v101
	s_nop 0
	v_cndmask_b32_e32 v60, v215, v60, vcc
	v_cmp_lt_u32_e32 vcc, s0, v102
	v_add_u32_e32 v102, 0xffffff32, v101
	s_nop 0
	v_cndmask_b32_e32 v45, v215, v45, vcc
	v_cmp_lt_u32_e32 vcc, s0, v102
	v_add_u32_e32 v102, 0xffffff17, v101
	s_nop 0
	v_cndmask_b32_e32 v61, v215, v61, vcc
	v_cmp_lt_u32_e32 vcc, s0, v102
	v_add_u32_e32 v102, 0xffffff37, v101
	s_nop 0
	v_cndmask_b32_e32 v46, v215, v46, vcc
	v_cmp_lt_u32_e32 vcc, s0, v102
	v_add_u32_e32 v102, 0xffffff18, v101
	s_nop 0
	v_cndmask_b32_e32 v62, v215, v62, vcc
	v_cmp_lt_u32_e32 vcc, s0, v102
	v_add_u32_e32 v102, 0xffffff38, v101
	s_nop 0
	v_cndmask_b32_e32 v47, v215, v47, vcc
	v_cmp_lt_u32_e32 vcc, s0, v102
	v_add_u32_e32 v102, 0xffffff19, v101
	s_nop 0
	v_cndmask_b32_e32 v63, v215, v63, vcc
	v_cmp_lt_u32_e32 vcc, s0, v102
	v_add_u32_e32 v102, 0xffffff39, v101
	s_nop 0
	v_cndmask_b32_e32 v48, v215, v48, vcc
	v_cmp_lt_u32_e32 vcc, s0, v102
	v_add_u32_e32 v102, 0xffffff1a, v101
	v_add_u32_e32 v101, 0xffffff3a, v101
	v_cndmask_b32_e32 v64, v215, v64, vcc
	v_cmp_lt_u32_e32 vcc, s0, v102
	s_nop 1
	v_cndmask_b32_e32 v49, v215, v49, vcc
	v_cmp_lt_u32_e32 vcc, s0, v101
	s_nop 1
	v_cndmask_b32_e32 v65, v215, v65, vcc

.Lprio_12:
	v_add_u32_e32 v204, s8, v94
	v_add_u32_e32 v205, s8, v95
	v_add_u32_e32 v248, s8, v96
	v_add_u32_e32 v249, s8, v97
	ds_read_b128 v[196:199], v204 offset:8192
	ds_read_b128 v[200:203], v205 offset:8192
	ds_read_b128 v[232:235], v248 offset:8192
	ds_read_b128 v[236:239], v249 offset:8192
	ds_read_b128 v[240:243], v204 offset:12288
	s_waitcnt lgkmcnt(5)
	v_add_f32_e32 v63, v63, v64
	v_fmac_f32_e32 v63, v100, v0
	v_cvt_pk_bf16_f32 v106, v34, v35
	v_cvt_pk_bf16_f32 v34, v39, v42
	v_cvt_pk_bf16_f32 v111, v43, v45
	v_cvt_pk_bf16_f32 v35, v44, v58
	v_cvt_pk_bf16_f32 v107, v36, v37
	v_cvt_pk_bf16_f32 v108, v102, v103
	v_cvt_pk_bf16_f32 v112, v46, v47
	v_cvt_pk_bf16_f32 v109, v104, v41
	v_cvt_pk_bf16_f32 v110, v38, v40
	s_waitcnt lgkmcnt(4)
	v_mfma_f32_32x32x16_bf16 v[18:33], v[196:199], v[106:109], v[18:33]
	ds_read_b128 v[244:247], v205 offset:12288
	v_cvt_pk_bf16_f32 v113, v48, v49
	v_cvt_pk_bf16_f32 v38, v50, v51
	v_cvt_pk_bf16_f32 v39, v52, v53
	v_cvt_pk_bf16_f32 v40, v54, v55
	v_cvt_pk_bf16_f32 v41, v56, v57
	s_waitcnt lgkmcnt(4)
	v_mfma_f32_32x32x16_bf16 v[18:33], v[200:203], v[110:113], v[18:33]
	ds_read_b128 v[196:199], v248 offset:12288
	v_cvt_pk_bf16_f32 v36, v59, v60
	v_cvt_pk_bf16_f32 v37, v61, v62
	v_mov_b32_e32 v100, v63
	s_waitcnt lgkmcnt(4)
	v_mfma_f32_32x32x16_bf16 v[18:33], v[232:235], v[38:41], v[18:33]
	ds_read_b128 v[200:203], v249 offset:12288
	s_waitcnt lgkmcnt(4)
	v_mfma_f32_32x32x16_bf16 v[18:33], v[236:239], v[34:37], v[18:33]
	s_waitcnt lgkmcnt(3)
	v_mfma_f32_32x32x16_bf16 v[2:17], v[240:243], v[106:109], v[2:17]
	s_waitcnt lgkmcnt(2)
	v_mfma_f32_32x32x16_bf16 v[2:17], v[244:247], v[110:113], v[2:17]
	s_waitcnt lgkmcnt(1)
	v_mfma_f32_32x32x16_bf16 v[2:17], v[196:199], v[38:41], v[2:17]
	s_waitcnt lgkmcnt(0)
	v_mfma_f32_32x32x16_bf16 v[2:17], v[200:203], v[34:37], v[2:17]
	s_branch .LBB0_409

.Lprio_17:
	v_add_u32_e32 v204, s4, v110
	v_add_u32_e32 v205, s4, v111
	v_add_u32_e32 v248, s4, v112
	v_add_u32_e32 v249, s4, v113
	ds_read_b128 v[196:199], v204 offset:8192
	ds_read_b128 v[200:203], v205 offset:8192
	ds_read_b128 v[232:235], v248 offset:8192
	ds_read_b128 v[236:239], v249 offset:8192
	ds_read_b128 v[240:243], v204 offset:12288
	s_waitcnt lgkmcnt(5)
	v_add_f32_e32 v63, v63, v64
	v_fmac_f32_e32 v63, v115, v0
	v_cvt_pk_bf16_f32 v70, v38, v40
	v_cvt_pk_bf16_f32 v38, v34, v35
	v_cvt_pk_bf16_f32 v34, v39, v42
	v_cvt_pk_bf16_f32 v71, v43, v58
	v_cvt_pk_bf16_f32 v35, v44, v45
	v_cvt_pk_bf16_f32 v50, v50, v51
	v_cvt_pk_bf16_f32 v51, v52, v53
	v_cvt_pk_bf16_f32 v39, v36, v37
	v_cvt_pk_bf16_f32 v52, v54, v55
	v_cvt_pk_bf16_f32 v36, v46, v47
	v_cvt_pk_bf16_f32 v53, v56, v57
	v_cvt_pk_bf16_f32 v72, v59, v60
	s_waitcnt lgkmcnt(4)
	v_mfma_f32_32x32x16_bf16 v[18:33], v[196:199], v[50:53], v[18:33]
	ds_read_b128 v[244:247], v205 offset:12288
	v_cvt_pk_bf16_f32 v73, v61, v62
	v_cvt_pk_bf16_f32 v40, v67, v68
	v_cvt_pk_bf16_f32 v41, v69, v41
	v_cvt_pk_bf16_f32 v37, v48, v49
	s_waitcnt lgkmcnt(4)
	v_mfma_f32_32x32x16_bf16 v[18:33], v[200:203], v[70:73], v[18:33]
	ds_read_b128 v[196:199], v248 offset:12288
	v_mov_b32_e32 v115, v63
	s_waitcnt lgkmcnt(4)
	v_mfma_f32_32x32x16_bf16 v[18:33], v[232:235], v[38:41], v[18:33]
	ds_read_b128 v[200:203], v249 offset:12288
	s_waitcnt lgkmcnt(4)
	v_mfma_f32_32x32x16_bf16 v[18:33], v[236:239], v[34:37], v[18:33]
	v_mov_b32_e32 v0, v66
	s_waitcnt lgkmcnt(3)
	v_mfma_f32_32x32x16_bf16 v[2:17], v[240:243], v[50:53], v[2:17]
	s_waitcnt lgkmcnt(2)
	v_mfma_f32_32x32x16_bf16 v[2:17], v[244:247], v[70:73], v[2:17]
	s_waitcnt lgkmcnt(1)
	v_mfma_f32_32x32x16_bf16 v[2:17], v[196:199], v[38:41], v[2:17]
	s_waitcnt lgkmcnt(0)
	v_mfma_f32_32x32x16_bf16 v[2:17], v[200:203], v[34:37], v[2:17]

.Lprio_16:
	s_and_b32 s4, s56, 0xc000
	v_or_b32_e32 v38, s4, v110
	s_waitcnt vmcnt(0)
	v_or_b32_e32 v204, s4, v111
	v_or_b32_e32 v205, s4, v112
	v_or_b32_e32 v248, s4, v113
	ds_read_b128 v[196:199], v38
	ds_read_b128 v[200:203], v204
	ds_read_b128 v[232:235], v38 offset:4096
	ds_read_b128 v[236:239], v204 offset:4096
	ds_read_b128 v[240:243], v205
	s_andn2_b64 vcc, exec, s[10:11]
	s_waitcnt lgkmcnt(4)
	v_mfma_f32_32x32x16_bf16 v[50:65], v[196:199], v[82:85], 0
	ds_read_b128 v[244:247], v205 offset:4096
	s_waitcnt lgkmcnt(4)
	v_mfma_f32_32x32x16_bf16 v[50:65], v[200:203], v[86:89], v[50:65]
	ds_read_b128 v[196:199], v248
	s_waitcnt lgkmcnt(4)
	v_mfma_f32_32x32x16_bf16 v[34:49], v[232:235], v[82:85], 0
	ds_read_b128 v[200:203], v248 offset:4096
	s_waitcnt lgkmcnt(4)
	v_mfma_f32_32x32x16_bf16 v[34:49], v[236:239], v[86:89], v[34:49]
	s_waitcnt lgkmcnt(3)
	v_mfma_f32_32x32x16_bf16 v[50:65], v[240:243], v[90:93], v[50:65]
	s_waitcnt lgkmcnt(2)
	v_mfma_f32_32x32x16_bf16 v[34:49], v[244:247], v[90:93], v[34:49]
	s_waitcnt lgkmcnt(1)
	v_mfma_f32_32x32x16_bf16 v[50:65], v[196:199], v[94:97], v[50:65]
	s_waitcnt lgkmcnt(0)
	v_mfma_f32_32x32x16_bf16 v[34:49], v[200:203], v[94:97], v[34:49]
	s_nop 1
	s_cbranch_vccnz .LBB0_474
	s_lshl_b32 s0, s5, 6
	s_sub_i32 s1, s54, s57
	s_add_i32 s0, s1, s0
	s_addk_i32 s0, 0xf000
	s_ashr_i32 s0, s0, 6
	v_sub_u32_e32 v66, s0, v105
	s_movk_i32 s0, 0x7c
	v_mul_lo_u32 v66, v66, s0
	v_add_u32_e32 v117, v114, v66
	ds_read_b32 v116, v117 offset:1056
	v_mov_b32_e32 v67, 0xff800000
	v_mov_b32_e32 v66, 0xff800000
	s_and_saveexec_b64 s[0:1], s[40:41]
	s_cbranch_execz .LBB0_443
	ds_read_b32 v66, v117 offset:928
	s_waitcnt lgkmcnt(0)
	v_add_f32_e32 v66, v50, v66
